# Hyena group RMSNorm tile loop: each tile's 16 loads issued one tile ahead (after the previous tile's first barrier), counted waits; first tile's loads in front of the loop
# speedup vs baseline: 1.0003x; 1.0003x over previous
.LBB0_781:
	v_readlane_b32 s0, v253, 57
	v_readlane_b32 s1, v253, 58
	v_readlane_b32 s44, v253, 23
	v_mov_b32_e32 v4, v252
	s_andn2_b64 vcc, exec, s[0:1]
	v_readlane_b32 s14, v254, 50
	v_readlane_b32 s52, v253, 31
	v_readlane_b32 s53, v253, 32
	v_readlane_b32 s15, v254, 51
	v_readlane_b32 s45, v253, 24
	v_readlane_b32 s46, v253, 25
	v_readlane_b32 s47, v253, 26
	v_readlane_b32 s48, v253, 27
	v_readlane_b32 s49, v253, 28
	v_readlane_b32 s50, v253, 29
	v_readlane_b32 s51, v253, 30
	v_readlane_b32 s54, v253, 33
	v_readlane_b32 s55, v253, 34
	v_readlane_b32 s56, v253, 35
	v_readlane_b32 s57, v253, 36
	v_readlane_b32 s58, v253, 37
	v_readlane_b32 s59, v253, 38
	s_cbranch_vccnz .LBB0_784
	v_ashrrev_i32_e32 v27, 6, v4
	v_and_b32_e32 v26, 63, v4
	v_lshlrev_b32_e32 v8, 4, v27
	s_movk_i32 s0, 0x1040
	v_lshlrev_b32_e32 v0, 1, v26
	v_mov_b32_e32 v1, 0
	v_lshlrev_b32_e32 v6, 2, v26
	v_mul_lo_u32 v34, v27, s0
	v_or_b32_e32 v9, 1, v8
	s_movk_i32 s0, 0x104
	v_lshl_add_u64 v[2:3], s[16:17], 0, v[0:1]
	v_add_u32_e32 v35, 0, v6
	v_mul_lo_u32 v36, v9, s0
	v_mov_b32_e32 v7, v1
	v_lshl_add_u32 v1, v27, 5, 0
	s_movk_i32 s0, 0x208
	s_mov_b32 s1, 0
	v_lshlrev_b32_e32 v25, 3, v27
	v_mad_u32_u24 v26, v26, s0, v1
	v_add_u32_e32 v34, v35, v34
	v_add_u32_e32 v35, v35, v36
	s_mov_b32 s0, 0x358637bd
	s_mov_b64 s[20:21], s[52:53]
	v_or_b32_e32 v10, 2, v8
	v_or_b32_e32 v11, 3, v8
	v_or_b32_e32 v12, 4, v8
	v_or_b32_e32 v13, 5, v8
	v_or_b32_e32 v14, 6, v8
	v_or_b32_e32 v15, 7, v8
	v_or_b32_e32 v16, 8, v8
	v_or_b32_e32 v17, 9, v8
	v_or_b32_e32 v18, 10, v8
	v_or_b32_e32 v19, 11, v8
	v_or_b32_e32 v20, 12, v8
	v_or_b32_e32 v21, 13, v8
	v_or_b32_e32 v22, 14, v8
	v_or_b32_e32 v23, 15, v8
	v_lshl_add_u32 v24, v4, 2, 0
	v_lshl_add_u64 v[4:5], s[84:85], 0, v[6:7]
	v_or_b32_e32 v27, 1, v25
	v_or_b32_e32 v28, 2, v25
	v_or_b32_e32 v29, 3, v25
	v_or_b32_e32 v30, 4, v25
	v_or_b32_e32 v31, 5, v25
	v_or_b32_e32 v32, 6, v25
	v_or_b32_e32 v33, 7, v25
	s_lshl_b32 s3, s78, 7
	s_lshl_b32 s8, s80, 7
	s_brev_b32 s2, 60
	v_mov_b64_e32 v[6:7], s[0:1]
	s_mov_b32 s9, 0x800000
	s_movk_i32 s10, 0x7fff
	s_mov_b32 s11, 0xffff0000
	v_add_u32_e32 v36, 0x400, v35
	v_add_u32_e32 v37, 0x800, v35
	v_add_u32_e32 v38, 0xc00, v35
	s_mov_b32 s12, s79
	s_mov_b32 s13, s78
	s_and_b32 s98, s3, 0x380
	s_and_b32 s100, s12, 0xffffffc0
	s_ashr_i32 s101, s100, 31
	v_add_u32_e32 v218, s98, v8
	v_ashrrev_i32_e32 v219, 31, v218
	v_lshl_add_u64 v[216:217], s[100:101], 1, v[2:3]
	v_lshlrev_b64 v[218:219], 14, v[218:219]
	v_lshl_add_u64 v[218:219], v[216:217], 0, v[218:219]
	global_load_ushort v200, v[218:219], off
	v_add_u32_e32 v218, s98, v9
	v_ashrrev_i32_e32 v219, 31, v218
	v_lshlrev_b64 v[218:219], 14, v[218:219]
	v_lshl_add_u64 v[218:219], v[216:217], 0, v[218:219]
	global_load_ushort v201, v[218:219], off
	v_add_u32_e32 v218, s98, v10
	v_ashrrev_i32_e32 v219, 31, v218
	v_lshlrev_b64 v[218:219], 14, v[218:219]
	v_lshl_add_u64 v[218:219], v[216:217], 0, v[218:219]
	global_load_ushort v202, v[218:219], off
	v_add_u32_e32 v218, s98, v11
	v_ashrrev_i32_e32 v219, 31, v218
	v_lshlrev_b64 v[218:219], 14, v[218:219]
	v_lshl_add_u64 v[218:219], v[216:217], 0, v[218:219]
	global_load_ushort v203, v[218:219], off
	v_add_u32_e32 v218, s98, v12
	v_ashrrev_i32_e32 v219, 31, v218
	v_lshlrev_b64 v[218:219], 14, v[218:219]
	v_lshl_add_u64 v[218:219], v[216:217], 0, v[218:219]
	global_load_ushort v204, v[218:219], off
	v_add_u32_e32 v218, s98, v13
	v_ashrrev_i32_e32 v219, 31, v218
	v_lshlrev_b64 v[218:219], 14, v[218:219]
	v_lshl_add_u64 v[218:219], v[216:217], 0, v[218:219]
	global_load_ushort v205, v[218:219], off
	v_add_u32_e32 v218, s98, v14
	v_ashrrev_i32_e32 v219, 31, v218
	v_lshlrev_b64 v[218:219], 14, v[218:219]
	v_lshl_add_u64 v[218:219], v[216:217], 0, v[218:219]
	global_load_ushort v206, v[218:219], off
	v_add_u32_e32 v218, s98, v15
	v_ashrrev_i32_e32 v219, 31, v218
	v_lshlrev_b64 v[218:219], 14, v[218:219]
	v_lshl_add_u64 v[218:219], v[216:217], 0, v[218:219]
	global_load_ushort v207, v[218:219], off
	v_add_u32_e32 v218, s98, v16
	v_ashrrev_i32_e32 v219, 31, v218
	v_lshlrev_b64 v[218:219], 14, v[218:219]
	v_lshl_add_u64 v[218:219], v[216:217], 0, v[218:219]
	global_load_ushort v208, v[218:219], off
	v_add_u32_e32 v218, s98, v17
	v_ashrrev_i32_e32 v219, 31, v218
	v_lshlrev_b64 v[218:219], 14, v[218:219]
	v_lshl_add_u64 v[218:219], v[216:217], 0, v[218:219]
	global_load_ushort v209, v[218:219], off
	v_add_u32_e32 v218, s98, v18
	v_ashrrev_i32_e32 v219, 31, v218
	v_lshlrev_b64 v[218:219], 14, v[218:219]
	v_lshl_add_u64 v[218:219], v[216:217], 0, v[218:219]
	global_load_ushort v210, v[218:219], off
	v_add_u32_e32 v218, s98, v19
	v_ashrrev_i32_e32 v219, 31, v218
	v_lshlrev_b64 v[218:219], 14, v[218:219]
	v_lshl_add_u64 v[218:219], v[216:217], 0, v[218:219]
	global_load_ushort v211, v[218:219], off
	v_add_u32_e32 v218, s98, v20
	v_ashrrev_i32_e32 v219, 31, v218
	v_lshlrev_b64 v[218:219], 14, v[218:219]
	v_lshl_add_u64 v[218:219], v[216:217], 0, v[218:219]
	global_load_ushort v212, v[218:219], off
	v_add_u32_e32 v218, s98, v21
	v_ashrrev_i32_e32 v219, 31, v218
	v_lshlrev_b64 v[218:219], 14, v[218:219]
	v_lshl_add_u64 v[218:219], v[216:217], 0, v[218:219]
	global_load_ushort v213, v[218:219], off
	v_add_u32_e32 v218, s98, v22
	v_ashrrev_i32_e32 v219, 31, v218
	v_lshlrev_b64 v[218:219], 14, v[218:219]
	v_lshl_add_u64 v[218:219], v[216:217], 0, v[218:219]
	global_load_ushort v214, v[218:219], off
	v_add_u32_e32 v218, s98, v23
	v_ashrrev_i32_e32 v219, 31, v218
	v_lshlrev_b64 v[218:219], 14, v[218:219]
	v_lshl_add_u64 v[216:217], v[216:217], 0, v[218:219]
	global_load_ushort v215, v[216:217], off
	s_waitcnt vmcnt(0)
.LBB0_783:
	s_and_b32 s0, s3, 0x380
	s_and_b32 s6, s12, 0xffffffc0
	s_ashr_i32 s7, s6, 31
	s_add_i32 s13, s13, s80
	s_add_i32 s12, s12, s14
	v_add_u32_e32 v44, s6, v25
	v_or_b32_e32 v39, s0, v0
	v_lshlrev_b32_e32 v39, 2, v39
	s_waitcnt vmcnt(8)
	v_lshlrev_b32_e32 v200, 16, v200
	ds_write_b32 v34, v200
	v_lshlrev_b32_e32 v201, 16, v201
	v_mul_f32_e32 v45, v201, v201
	v_fmac_f32_e32 v45, v200, v200
	v_lshlrev_b32_e32 v202, 16, v202
	ds_write2_b32 v35, v201, v202 offset1:65
	v_fmac_f32_e32 v45, v202, v202
	v_lshlrev_b32_e32 v203, 16, v203
	v_fmac_f32_e32 v45, v203, v203
	v_lshlrev_b32_e32 v204, 16, v204
	ds_write2_b32 v35, v203, v204 offset0:130 offset1:195
	v_fmac_f32_e32 v45, v204, v204
	v_lshlrev_b32_e32 v205, 16, v205
	v_fmac_f32_e32 v45, v205, v205
	v_lshlrev_b32_e32 v206, 16, v206
	ds_write2_b32 v36, v205, v206 offset0:4 offset1:69
	v_fmac_f32_e32 v45, v206, v206
	v_lshlrev_b32_e32 v207, 16, v207
	v_fmac_f32_e32 v45, v207, v207
	v_lshlrev_b32_e32 v208, 16, v208
	ds_write2_b32 v36, v207, v208 offset0:134 offset1:199
	v_fmac_f32_e32 v45, v208, v208
	v_lshlrev_b32_e32 v209, 16, v209
	v_fmac_f32_e32 v45, v209, v209
	v_lshlrev_b32_e32 v210, 16, v210
	ds_write2_b32 v37, v209, v210 offset0:8 offset1:73
	v_fmac_f32_e32 v45, v210, v210
	v_lshlrev_b32_e32 v211, 16, v211
	v_fmac_f32_e32 v45, v211, v211
	v_lshlrev_b32_e32 v212, 16, v212
	ds_write2_b32 v37, v211, v212 offset0:138 offset1:203
	v_fmac_f32_e32 v45, v212, v212
	v_lshlrev_b32_e32 v213, 16, v213
	v_fmac_f32_e32 v45, v213, v213
	v_lshlrev_b32_e32 v214, 16, v214
	ds_write2_b32 v38, v213, v214 offset0:12 offset1:77
	v_fmac_f32_e32 v45, v214, v214
	v_lshlrev_b32_e32 v215, 16, v215
	ds_write_b32 v35, v215 offset:3640
	v_fmac_f32_e32 v45, v215, v215
	ds_write_b32 v24, v45 offset:33280
	s_waitcnt lgkmcnt(0)
	s_barrier
	global_load_dwordx2 v[80:81], v39, s[20:21]
	s_add_i32 s98, s3, s8
	s_and_b32 s98, s98, 0x380
	s_and_b32 s100, s12, 0xffffffc0
	s_ashr_i32 s101, s100, 31
	v_add_u32_e32 v218, s98, v8
	v_ashrrev_i32_e32 v219, 31, v218
	v_lshl_add_u64 v[216:217], s[100:101], 1, v[2:3]
	v_lshlrev_b64 v[218:219], 14, v[218:219]
	v_lshl_add_u64 v[218:219], v[216:217], 0, v[218:219]
	global_load_ushort v200, v[218:219], off
	v_add_u32_e32 v218, s98, v9
	v_ashrrev_i32_e32 v219, 31, v218
	v_lshlrev_b64 v[218:219], 14, v[218:219]
	v_lshl_add_u64 v[218:219], v[216:217], 0, v[218:219]
	global_load_ushort v201, v[218:219], off
	v_add_u32_e32 v218, s98, v10
	v_ashrrev_i32_e32 v219, 31, v218
	v_lshlrev_b64 v[218:219], 14, v[218:219]
	v_lshl_add_u64 v[218:219], v[216:217], 0, v[218:219]
	global_load_ushort v202, v[218:219], off
	v_add_u32_e32 v218, s98, v11
	v_ashrrev_i32_e32 v219, 31, v218
	v_lshlrev_b64 v[218:219], 14, v[218:219]
	v_lshl_add_u64 v[218:219], v[216:217], 0, v[218:219]
	global_load_ushort v203, v[218:219], off
	v_add_u32_e32 v218, s98, v12
	v_ashrrev_i32_e32 v219, 31, v218
	v_lshlrev_b64 v[218:219], 14, v[218:219]
	v_lshl_add_u64 v[218:219], v[216:217], 0, v[218:219]
	global_load_ushort v204, v[218:219], off
	v_add_u32_e32 v218, s98, v13
	v_ashrrev_i32_e32 v219, 31, v218
	v_lshlrev_b64 v[218:219], 14, v[218:219]
	v_lshl_add_u64 v[218:219], v[216:217], 0, v[218:219]
	global_load_ushort v205, v[218:219], off
	v_add_u32_e32 v218, s98, v14
	v_ashrrev_i32_e32 v219, 31, v218
	v_lshlrev_b64 v[218:219], 14, v[218:219]
	v_lshl_add_u64 v[218:219], v[216:217], 0, v[218:219]
	global_load_ushort v206, v[218:219], off
	v_add_u32_e32 v218, s98, v15
	v_ashrrev_i32_e32 v219, 31, v218
	v_lshlrev_b64 v[218:219], 14, v[218:219]
	v_lshl_add_u64 v[218:219], v[216:217], 0, v[218:219]
	global_load_ushort v207, v[218:219], off
	v_add_u32_e32 v218, s98, v16
	v_ashrrev_i32_e32 v219, 31, v218
	v_lshlrev_b64 v[218:219], 14, v[218:219]
	v_lshl_add_u64 v[218:219], v[216:217], 0, v[218:219]
	global_load_ushort v208, v[218:219], off
	v_add_u32_e32 v218, s98, v17
	v_ashrrev_i32_e32 v219, 31, v218
	v_lshlrev_b64 v[218:219], 14, v[218:219]
	v_lshl_add_u64 v[218:219], v[216:217], 0, v[218:219]
	global_load_ushort v209, v[218:219], off
	v_add_u32_e32 v218, s98, v18
	v_ashrrev_i32_e32 v219, 31, v218
	v_lshlrev_b64 v[218:219], 14, v[218:219]
	v_lshl_add_u64 v[218:219], v[216:217], 0, v[218:219]
	global_load_ushort v210, v[218:219], off
	v_add_u32_e32 v218, s98, v19
	v_ashrrev_i32_e32 v219, 31, v218
	v_lshlrev_b64 v[218:219], 14, v[218:219]
	v_lshl_add_u64 v[218:219], v[216:217], 0, v[218:219]
	global_load_ushort v211, v[218:219], off
	v_add_u32_e32 v218, s98, v20
	v_ashrrev_i32_e32 v219, 31, v218
	v_lshlrev_b64 v[218:219], 14, v[218:219]
	v_lshl_add_u64 v[218:219], v[216:217], 0, v[218:219]
	global_load_ushort v212, v[218:219], off
	v_add_u32_e32 v218, s98, v21
	v_ashrrev_i32_e32 v219, 31, v218
	v_lshlrev_b64 v[218:219], 14, v[218:219]
	v_lshl_add_u64 v[218:219], v[216:217], 0, v[218:219]
	global_load_ushort v213, v[218:219], off
	v_add_u32_e32 v218, s98, v22
	v_ashrrev_i32_e32 v219, 31, v218
	v_lshlrev_b64 v[218:219], 14, v[218:219]
	v_lshl_add_u64 v[218:219], v[216:217], 0, v[218:219]
	global_load_ushort v214, v[218:219], off
	v_add_u32_e32 v218, s98, v23
	v_ashrrev_i32_e32 v219, 31, v218
	v_lshlrev_b64 v[218:219], 14, v[218:219]
	v_lshl_add_u64 v[216:217], v[216:217], 0, v[218:219]
	global_load_ushort v215, v[216:217], off
	s_lshl_b32 s0, s0, 1
	v_ashrrev_i32_e32 v45, 31, v44
	v_lshl_add_u64 v[82:83], v[4:5], 0, s[0:1]
	v_lshlrev_b64 v[44:45], 12, v[44:45]
	ds_read2_b64 v[40:43], v26 offset1:1
	ds_read2_b32 v[84:85], v26 offset0:65 offset1:66
	v_lshl_add_u64 v[86:87], v[82:83], 0, v[44:45]
	ds_read_b128 v[44:47], v1 offset:33280
	ds_read_b128 v[48:51], v1 offset:33296
	ds_read_b128 v[52:55], v1 offset:33536
	ds_read_b128 v[56:59], v1 offset:33792
	ds_read_b128 v[60:63], v1 offset:34048
	ds_read_b128 v[64:67], v1 offset:34304
	s_waitcnt lgkmcnt(5)
	v_pk_add_f32 v[44:45], v[44:45], 0 op_sel_hi:[1,0]
	ds_read_b128 v[68:71], v1 offset:34560
	ds_read_b128 v[72:75], v1 offset:34816
	s_waitcnt lgkmcnt(5)
	v_pk_add_f32 v[44:45], v[44:45], v[52:53]
	ds_read_b128 v[76:79], v1 offset:35072
	s_waitcnt lgkmcnt(5)
	v_pk_add_f32 v[44:45], v[44:45], v[56:57]
	v_pk_add_f32 v[46:47], v[46:47], 0 op_sel_hi:[1,0]
	s_waitcnt lgkmcnt(4)
	v_pk_add_f32 v[44:45], v[44:45], v[60:61]
	v_pk_add_f32 v[46:47], v[46:47], v[54:55]
	s_waitcnt lgkmcnt(3)
	v_pk_add_f32 v[44:45], v[44:45], v[64:65]
	v_pk_add_f32 v[46:47], v[46:47], v[58:59]
	s_waitcnt lgkmcnt(2)
	v_pk_add_f32 v[44:45], v[44:45], v[68:69]
	v_pk_add_f32 v[46:47], v[46:47], v[62:63]
	s_waitcnt lgkmcnt(1)
	v_pk_add_f32 v[44:45], v[44:45], v[72:73]
	v_pk_add_f32 v[46:47], v[46:47], v[66:67]
	s_waitcnt lgkmcnt(0)
	v_pk_add_f32 v[44:45], v[44:45], v[76:77]
	v_pk_add_f32 v[46:47], v[46:47], v[70:71]
	v_pk_fma_f32 v[44:45], v[44:45], s[2:3], v[6:7] op_sel_hi:[1,0,0]
	v_pk_add_f32 v[46:47], v[46:47], v[74:75]
	v_mul_f32_e32 v39, 0x4b800000, v44
	v_cmp_gt_f32_e64 s[4:5], s9, v44
	v_cmp_gt_f32_e32 vcc, s9, v45
	v_pk_add_f32 v[46:47], v[46:47], v[78:79]
	v_cndmask_b32_e64 v39, v44, v39, s[4:5]
	v_rsq_f32_e32 v39, v39
	v_pk_fma_f32 v[46:47], v[46:47], s[2:3], v[6:7] op_sel_hi:[1,0,0]
	v_pk_add_f32 v[48:49], v[48:49], 0 op_sel_hi:[1,0]
	v_mul_f32_e32 v44, 0x45800000, v39
	v_cndmask_b32_e64 v39, v39, v44, s[4:5]
	v_mul_f32_e32 v40, v40, v39
	v_mul_f32_e32 v39, v84, v39
	v_cmp_gt_f32_e64 s[4:5], s9, v46
	s_waitcnt vmcnt(16)
	v_mul_f32_e32 v40, v80, v40
	v_mul_f32_e32 v39, v81, v39
	v_bfe_u32 v44, v40, 16, 1
	v_add3_u32 v40, v40, v44, s10
	v_bfe_u32 v44, v39, 16, 1
	v_lshrrev_b32_e32 v40, 16, v40
	v_add3_u32 v39, v39, v44, s10
	v_and_or_b32 v39, v39, s11, v40
	global_store_dword v[86:87], v39, off
	v_mul_f32_e32 v39, 0x4b800000, v45
	v_cndmask_b32_e32 v39, v45, v39, vcc
	v_rsq_f32_e32 v39, v39
	v_add_u32_e32 v44, s6, v28
	v_ashrrev_i32_e32 v45, 31, v44
	v_lshlrev_b64 v[44:45], 12, v[44:45]
	v_mul_f32_e32 v40, 0x45800000, v39
	v_cndmask_b32_e32 v39, v39, v40, vcc
	v_mul_f32_e32 v40, v41, v39
	v_mul_f32_e32 v40, v80, v40
	v_mul_f32_e32 v39, v85, v39
	v_mul_f32_e32 v39, v81, v39
	v_bfe_u32 v41, v40, 16, 1
	v_add3_u32 v40, v40, v41, s10
	v_bfe_u32 v41, v39, 16, 1
	v_lshrrev_b32_e32 v40, 16, v40
	v_add3_u32 v39, v39, v41, s10
	v_and_or_b32 v39, v39, s11, v40
	v_add_u32_e32 v40, s6, v27
	v_ashrrev_i32_e32 v41, 31, v40
	v_lshlrev_b64 v[40:41], 12, v[40:41]
	v_lshl_add_u64 v[40:41], v[82:83], 0, v[40:41]
	global_store_dword v[40:41], v39, off
	v_mul_f32_e32 v39, 0x4b800000, v46
	v_cndmask_b32_e64 v39, v46, v39, s[4:5]
	v_rsq_f32_e32 v39, v39
	ds_read2_b32 v[40:41], v26 offset0:67 offset1:68
	v_lshl_add_u64 v[44:45], v[82:83], 0, v[44:45]
	v_cmp_gt_f32_e32 vcc, s9, v47
	v_mul_f32_e32 v46, 0x45800000, v39
	v_cndmask_b32_e64 v39, v39, v46, s[4:5]
	v_mul_f32_e32 v42, v42, v39
	v_mul_f32_e32 v42, v80, v42
	s_waitcnt lgkmcnt(0)
	v_mul_f32_e32 v39, v40, v39
	v_mul_f32_e32 v39, v81, v39
	v_bfe_u32 v40, v42, 16, 1
	v_add3_u32 v40, v42, v40, s10
	v_bfe_u32 v42, v39, 16, 1
	v_lshrrev_b32_e32 v40, 16, v40
	v_add3_u32 v39, v39, v42, s10
	v_and_or_b32 v39, v39, s11, v40
	global_store_dword v[44:45], v39, off
	v_mul_f32_e32 v39, 0x4b800000, v47
	v_cndmask_b32_e32 v39, v47, v39, vcc
	v_rsq_f32_e32 v39, v39
	v_add_u32_e32 v44, s6, v30
	v_ashrrev_i32_e32 v45, 31, v44
	v_lshlrev_b64 v[44:45], 12, v[44:45]
	v_mul_f32_e32 v40, 0x45800000, v39
	v_cndmask_b32_e32 v39, v39, v40, vcc
	v_mul_f32_e32 v40, v43, v39
	v_mul_f32_e32 v40, v80, v40
	v_mul_f32_e32 v39, v41, v39
	v_mul_f32_e32 v39, v81, v39
	v_bfe_u32 v41, v40, 16, 1
	v_add3_u32 v40, v40, v41, s10
	v_bfe_u32 v41, v39, 16, 1
	v_lshrrev_b32_e32 v40, 16, v40
	v_add3_u32 v39, v39, v41, s10
	v_and_or_b32 v39, v39, s11, v40
	v_add_u32_e32 v40, s6, v29
	v_ashrrev_i32_e32 v41, 31, v40
	v_lshlrev_b64 v[40:41], 12, v[40:41]
	v_lshl_add_u64 v[40:41], v[82:83], 0, v[40:41]
	global_store_dword v[40:41], v39, off
	ds_read2_b64 v[40:43], v26 offset0:2 offset1:3
	ds_read2_b32 v[76:77], v26 offset0:69 offset1:70
	v_lshl_add_u64 v[78:79], v[82:83], 0, v[44:45]
	ds_read_b128 v[44:47], v1 offset:33552
	ds_read_b128 v[52:55], v1 offset:33808
	ds_read_b128 v[56:59], v1 offset:34064
	ds_read_b128 v[60:63], v1 offset:34320
	ds_read_b128 v[64:67], v1 offset:34576
	ds_read_b128 v[68:71], v1 offset:34832
	s_waitcnt lgkmcnt(5)
	v_pk_add_f32 v[44:45], v[48:49], v[44:45]
	ds_read_b128 v[72:75], v1 offset:35088
	s_waitcnt lgkmcnt(5)
	v_pk_add_f32 v[44:45], v[44:45], v[52:53]
	v_pk_add_f32 v[48:49], v[50:51], 0 op_sel_hi:[1,0]
	s_waitcnt lgkmcnt(4)
	v_pk_add_f32 v[44:45], v[44:45], v[56:57]
	v_pk_add_f32 v[46:47], v[48:49], v[46:47]
	s_waitcnt lgkmcnt(3)
	v_pk_add_f32 v[44:45], v[44:45], v[60:61]
	v_pk_add_f32 v[46:47], v[46:47], v[54:55]
	s_waitcnt lgkmcnt(2)
	v_pk_add_f32 v[44:45], v[44:45], v[64:65]
	v_pk_add_f32 v[46:47], v[46:47], v[58:59]
	s_waitcnt lgkmcnt(1)
	v_pk_add_f32 v[44:45], v[44:45], v[68:69]
	v_pk_add_f32 v[46:47], v[46:47], v[62:63]
	s_waitcnt lgkmcnt(0)
	v_pk_add_f32 v[44:45], v[44:45], v[72:73]
	v_pk_add_f32 v[46:47], v[46:47], v[66:67]
	v_pk_fma_f32 v[44:45], v[44:45], s[2:3], v[6:7] op_sel_hi:[1,0,0]
	v_pk_add_f32 v[46:47], v[46:47], v[70:71]
	v_mul_f32_e32 v39, 0x4b800000, v44
	v_cmp_gt_f32_e64 s[4:5], s9, v44
	v_cmp_gt_f32_e32 vcc, s9, v45
	v_pk_add_f32 v[46:47], v[46:47], v[74:75]
	v_cndmask_b32_e64 v39, v44, v39, s[4:5]
	v_rsq_f32_e32 v39, v39
	v_pk_fma_f32 v[46:47], v[46:47], s[2:3], v[6:7] op_sel_hi:[1,0,0]
	s_add_i32 s3, s3, s8
	s_cmpk_gt_i32 s13, 0x3ff
	v_mul_f32_e32 v44, 0x45800000, v39
	v_cndmask_b32_e64 v39, v39, v44, s[4:5]
	v_mul_f32_e32 v40, v40, v39
	v_mul_f32_e32 v40, v80, v40
	v_mul_f32_e32 v39, v76, v39
	v_mul_f32_e32 v39, v81, v39
	v_bfe_u32 v44, v40, 16, 1
	v_add3_u32 v40, v40, v44, s10
	v_bfe_u32 v44, v39, 16, 1
	v_lshrrev_b32_e32 v40, 16, v40
	v_add3_u32 v39, v39, v44, s10
	v_and_or_b32 v39, v39, s11, v40
	global_store_dword v[78:79], v39, off
	v_mul_f32_e32 v39, 0x4b800000, v45
	v_cndmask_b32_e32 v39, v45, v39, vcc
	v_rsq_f32_e32 v39, v39
	v_cmp_gt_f32_e64 s[4:5], s9, v46
	v_add_u32_e32 v44, s6, v32
	v_ashrrev_i32_e32 v45, 31, v44
	v_mul_f32_e32 v40, 0x45800000, v39
	v_cndmask_b32_e32 v39, v39, v40, vcc
	v_mul_f32_e32 v40, v41, v39
	v_mul_f32_e32 v40, v80, v40
	v_mul_f32_e32 v39, v77, v39
	v_mul_f32_e32 v39, v81, v39
	v_bfe_u32 v41, v40, 16, 1
	v_add3_u32 v40, v40, v41, s10
	v_bfe_u32 v41, v39, 16, 1
	v_lshrrev_b32_e32 v40, 16, v40
	v_add3_u32 v39, v39, v41, s10
	v_and_or_b32 v39, v39, s11, v40
	v_add_u32_e32 v40, s6, v31
	v_ashrrev_i32_e32 v41, 31, v40
	v_lshlrev_b64 v[40:41], 12, v[40:41]
	v_lshl_add_u64 v[40:41], v[82:83], 0, v[40:41]
	global_store_dword v[40:41], v39, off
	v_mul_f32_e32 v39, 0x4b800000, v46
	v_cndmask_b32_e64 v39, v46, v39, s[4:5]
	v_rsq_f32_e32 v39, v39
	ds_read2_b32 v[40:41], v26 offset0:71 offset1:72
	v_lshlrev_b64 v[44:45], 12, v[44:45]
	v_lshl_add_u64 v[44:45], v[82:83], 0, v[44:45]
	v_mul_f32_e32 v46, 0x45800000, v39
	v_cndmask_b32_e64 v39, v39, v46, s[4:5]
	v_mul_f32_e32 v42, v42, v39
	v_mul_f32_e32 v42, v80, v42
	s_waitcnt lgkmcnt(0)
	v_mul_f32_e32 v39, v40, v39
	v_mul_f32_e32 v39, v81, v39
	v_bfe_u32 v40, v42, 16, 1
	v_add3_u32 v40, v42, v40, s10
	v_bfe_u32 v42, v39, 16, 1
	v_lshrrev_b32_e32 v40, 16, v40
	v_add3_u32 v39, v39, v42, s10
	v_and_or_b32 v39, v39, s11, v40
	v_cmp_gt_f32_e32 vcc, s9, v47
	global_store_dword v[44:45], v39, off
	v_mul_f32_e32 v39, 0x4b800000, v47
	v_cndmask_b32_e32 v39, v47, v39, vcc
	v_rsq_f32_e32 v39, v39
	s_nop 0
	v_mul_f32_e32 v40, 0x45800000, v39
	v_cndmask_b32_e32 v39, v39, v40, vcc
	v_mul_f32_e32 v40, v43, v39
	v_mul_f32_e32 v40, v80, v40
	v_mul_f32_e32 v39, v41, v39
	v_mul_f32_e32 v39, v81, v39
	v_bfe_u32 v41, v40, 16, 1
	v_add3_u32 v40, v40, v41, s10
	v_bfe_u32 v41, v39, 16, 1
	v_lshrrev_b32_e32 v40, 16, v40
	v_add3_u32 v39, v39, v41, s10
	v_and_or_b32 v39, v39, s11, v40
	v_add_u32_e32 v40, s6, v33
	v_ashrrev_i32_e32 v41, 31, v40
	v_lshlrev_b64 v[40:41], 12, v[40:41]
	v_lshl_add_u64 v[40:41], v[82:83], 0, v[40:41]
	global_store_dword v[40:41], v39, off
	s_barrier
	s_cbranch_scc0 .LBB0_783
